# v81 with the grid-barrier pollers backing off s_sleep 2 instead of 4
# speedup vs baseline: 1.0074x; 1.0033x over previous
.LBB0_14:
	s_sleep 2
	global_load_dword v3, v0, s[2:3] offset:32 sc1
	s_waitcnt vmcnt(0)
	v_and_b32_e32 v3, 0xffff0000, v3
	v_cmp_ne_u32_e32 vcc, v3, v2
	s_or_b64 s[4:5], vcc, s[4:5]
	s_andn2_b64 exec, exec, s[4:5]
	s_cbranch_execnz .LBB0_14

.LBB0_115:
	global_load_dword v15, v16, s[4:5] sc1
	s_waitcnt lgkmcnt(0)
	global_load_dword v0, v16, s[6:7] sc1
	global_load_dword v1, v16, s[8:9] sc1
	global_load_dword v2, v16, s[10:11] sc1
	global_load_dword v3, v16, s[12:13] sc1
	global_load_dword v4, v16, s[14:15] sc1
	global_load_dword v5, v16, s[16:17] sc1
	global_load_dword v6, v16, s[18:19] sc1
	global_load_dword v7, v16, s[20:21] sc1
	global_load_dword v8, v16, s[22:23] sc1
	global_load_dword v9, v16, s[24:25] sc1
	global_load_dword v10, v16, s[26:27] sc1
	global_load_dword v11, v16, s[28:29] sc1
	global_load_dword v12, v16, s[30:31] sc1
	global_load_dword v13, v16, s[34:35] sc1
	global_load_dword v14, v16, s[36:37] sc1
	s_mov_b64 s[38:39], -1
	s_mov_b64 s[40:41], -1
	s_waitcnt vmcnt(14)
	v_add_u32_e32 v17, v0, v15
	s_waitcnt vmcnt(13)
	v_add_u32_e32 v17, v17, v1
	s_waitcnt vmcnt(12)
	v_add_u32_e32 v17, v17, v2
	s_waitcnt vmcnt(11)
	v_add_u32_e32 v17, v17, v3
	s_waitcnt vmcnt(10)
	v_add_u32_e32 v17, v17, v4
	s_waitcnt vmcnt(9)
	v_add_u32_e32 v17, v17, v5
	s_waitcnt vmcnt(8)
	v_add_u32_e32 v17, v17, v6
	s_waitcnt vmcnt(7)
	v_add_u32_e32 v17, v17, v7
	s_waitcnt vmcnt(6)
	v_add_u32_e32 v17, v17, v8
	s_waitcnt vmcnt(5)
	v_add_u32_e32 v17, v17, v9
	s_waitcnt vmcnt(4)
	v_add_u32_e32 v17, v17, v10
	s_waitcnt vmcnt(3)
	v_add_u32_e32 v17, v17, v11
	s_waitcnt vmcnt(2)
	v_add_u32_e32 v17, v17, v12
	s_waitcnt vmcnt(1)
	v_add_u32_e32 v17, v17, v13
	s_waitcnt vmcnt(0)
	v_add_u32_e32 v17, v17, v14
	v_cmp_eq_u32_e32 vcc, s33, v17
	s_cbranch_vccnz .LBB0_114
	s_and_b32 s38, s44, 0xff
	s_cmp_eq_u32 s38, 0
	s_mov_b64 s[38:39], -1
	s_mov_b64 s[42:43], -1
	s_sleep 2
	s_cbranch_scc0 .LBB0_119
	global_load_dword v17, v16, s[2:3] sc1
	s_waitcnt vmcnt(0)
	v_cmp_eq_u32_e32 vcc, 0, v17
	s_cbranch_vccnz .LBB0_121
	s_mov_b64 s[42:43], 0

.LBB0_133:
	s_and_b32 s18, s22, 0xff
	s_mov_b64 s[16:17], -1
	s_cmp_lg_u32 s18, 0
	s_mov_b64 s[20:21], -1
	s_sleep 2
	s_cbranch_scc1 .LBB0_136
	global_load_dword v2, v0, s[8:9] sc1
	s_waitcnt vmcnt(0)
	v_cmp_eq_u32_e32 vcc, 0, v2
	s_cbranch_vccnz .LBB0_138
	s_mov_b64 s[20:21], 0
	s_mov_b64 s[18:19], -1

.LBB0_150:
	s_and_b32 s16, s22, 0xff
	s_cmp_lg_u32 s16, 0
	s_mov_b64 s[18:19], -1
	s_sleep 2
	s_cbranch_scc1 .LBB0_153
	global_load_dword v1, v0, s[8:9] sc1
	s_waitcnt vmcnt(0)
	v_cmp_eq_u32_e32 vcc, 0, v1
	s_cbranch_vccnz .LBB0_155
	s_mov_b64 s[18:19], 0
	s_mov_b64 s[16:17], -1

.LBB0_571:
	global_load_dword v15, v16, s[6:7] sc1
	s_waitcnt lgkmcnt(0)
	global_load_dword v0, v16, s[8:9] sc1
	global_load_dword v1, v16, s[10:11] sc1
	global_load_dword v2, v16, s[12:13] sc1
	global_load_dword v3, v16, s[14:15] sc1
	global_load_dword v4, v16, s[16:17] sc1
	global_load_dword v5, v16, s[18:19] sc1
	global_load_dword v6, v16, s[20:21] sc1
	global_load_dword v7, v16, s[22:23] sc1
	global_load_dword v8, v16, s[24:25] sc1
	global_load_dword v9, v16, s[26:27] sc1
	global_load_dword v10, v16, s[28:29] sc1
	global_load_dword v11, v16, s[30:31] sc1
	global_load_dword v12, v16, s[34:35] sc1
	global_load_dword v13, v16, s[36:37] sc1
	global_load_dword v14, v16, s[38:39] sc1
	s_mov_b64 s[40:41], -1
	s_mov_b64 s[42:43], -1
	s_waitcnt vmcnt(14)
	v_add_u32_e32 v17, v0, v15
	s_waitcnt vmcnt(13)
	v_add_u32_e32 v17, v17, v1
	s_waitcnt vmcnt(12)
	v_add_u32_e32 v17, v17, v2
	s_waitcnt vmcnt(11)
	v_add_u32_e32 v17, v17, v3
	s_waitcnt vmcnt(10)
	v_add_u32_e32 v17, v17, v4
	s_waitcnt vmcnt(9)
	v_add_u32_e32 v17, v17, v5
	s_waitcnt vmcnt(8)
	v_add_u32_e32 v17, v17, v6
	s_waitcnt vmcnt(7)
	v_add_u32_e32 v17, v17, v7
	s_waitcnt vmcnt(6)
	v_add_u32_e32 v17, v17, v8
	s_waitcnt vmcnt(5)
	v_add_u32_e32 v17, v17, v9
	s_waitcnt vmcnt(4)
	v_add_u32_e32 v17, v17, v10
	s_waitcnt vmcnt(3)
	v_add_u32_e32 v17, v17, v11
	s_waitcnt vmcnt(2)
	v_add_u32_e32 v17, v17, v12
	s_waitcnt vmcnt(1)
	v_add_u32_e32 v17, v17, v13
	s_waitcnt vmcnt(0)
	v_add_u32_e32 v17, v17, v14
	v_cmp_eq_u32_e32 vcc, s33, v17
	s_cbranch_vccnz .LBB0_570
	s_and_b32 s40, s46, 0xff
	s_cmp_eq_u32 s40, 0
	s_mov_b64 s[40:41], -1
	s_mov_b64 s[44:45], -1
	s_sleep 2
	s_cbranch_scc0 .LBB0_575
	global_load_dword v17, v16, s[2:3] sc1
	s_waitcnt vmcnt(0)
	v_cmp_eq_u32_e32 vcc, 0, v17
	s_cbranch_vccnz .LBB0_577
	s_mov_b64 s[44:45], 0

.LBB0_589:
	s_and_b32 s20, s24, 0xff
	s_mov_b64 s[18:19], -1
	s_cmp_lg_u32 s20, 0
	s_mov_b64 s[22:23], -1
	s_sleep 2
	s_cbranch_scc1 .LBB0_592
	global_load_dword v2, v0, s[10:11] sc1
	s_waitcnt vmcnt(0)
	v_cmp_eq_u32_e32 vcc, 0, v2
	s_cbranch_vccnz .LBB0_594
	s_mov_b64 s[22:23], 0
	s_mov_b64 s[20:21], -1

.LBB0_606:
	s_and_b32 s18, s24, 0xff
	s_cmp_lg_u32 s18, 0
	s_mov_b64 s[20:21], -1
	s_sleep 2
	s_cbranch_scc1 .LBB0_609
	global_load_dword v1, v0, s[10:11] sc1
	s_waitcnt vmcnt(0)
	v_cmp_eq_u32_e32 vcc, 0, v1
	s_cbranch_vccnz .LBB0_611
	s_mov_b64 s[20:21], 0
	s_mov_b64 s[18:19], -1

.LBB0_658:
	global_load_dword v15, v16, s[12:13] sc1
	s_waitcnt lgkmcnt(0)
	global_load_dword v0, v16, s[14:15] sc1
	global_load_dword v1, v16, s[16:17] sc1
	global_load_dword v2, v16, s[18:19] sc1
	global_load_dword v3, v16, s[20:21] sc1
	global_load_dword v4, v16, s[22:23] sc1
	global_load_dword v5, v16, s[24:25] sc1
	global_load_dword v6, v16, s[26:27] sc1
	global_load_dword v7, v16, s[28:29] sc1
	global_load_dword v8, v16, s[30:31] sc1
	global_load_dword v9, v16, s[34:35] sc1
	global_load_dword v10, v16, s[36:37] sc1
	global_load_dword v11, v16, s[38:39] sc1
	global_load_dword v12, v16, s[40:41] sc1
	global_load_dword v13, v16, s[42:43] sc1
	global_load_dword v14, v16, s[44:45] sc1
	s_mov_b64 s[46:47], -1
	s_mov_b64 s[48:49], -1
	s_waitcnt vmcnt(14)
	v_add_u32_e32 v17, v0, v15
	s_waitcnt vmcnt(13)
	v_add_u32_e32 v17, v17, v1
	s_waitcnt vmcnt(12)
	v_add_u32_e32 v17, v17, v2
	s_waitcnt vmcnt(11)
	v_add_u32_e32 v17, v17, v3
	s_waitcnt vmcnt(10)
	v_add_u32_e32 v17, v17, v4
	s_waitcnt vmcnt(9)
	v_add_u32_e32 v17, v17, v5
	s_waitcnt vmcnt(8)
	v_add_u32_e32 v17, v17, v6
	s_waitcnt vmcnt(7)
	v_add_u32_e32 v17, v17, v7
	s_waitcnt vmcnt(6)
	v_add_u32_e32 v17, v17, v8
	s_waitcnt vmcnt(5)
	v_add_u32_e32 v17, v17, v9
	s_waitcnt vmcnt(4)
	v_add_u32_e32 v17, v17, v10
	s_waitcnt vmcnt(3)
	v_add_u32_e32 v17, v17, v11
	s_waitcnt vmcnt(2)
	v_add_u32_e32 v17, v17, v12
	s_waitcnt vmcnt(1)
	v_add_u32_e32 v17, v17, v13
	s_waitcnt vmcnt(0)
	v_add_u32_e32 v17, v17, v14
	v_cmp_eq_u32_e32 vcc, s52, v17
	s_cbranch_vccnz .LBB0_657
	s_and_b32 s46, s53, 0xff
	s_cmp_eq_u32 s46, 0
	s_mov_b64 s[46:47], -1
	s_mov_b64 s[50:51], -1
	s_sleep 2
	s_cbranch_scc0 .LBB0_662
	global_load_dword v17, v16, s[10:11] sc1
	s_waitcnt vmcnt(0)
	v_cmp_eq_u32_e32 vcc, 0, v17
	s_cbranch_vccnz .LBB0_664
	s_mov_b64 s[50:51], 0

.LBB0_676:
	s_and_b32 s26, s30, 0xff
	s_mov_b64 s[24:25], -1
	s_cmp_lg_u32 s26, 0
	s_mov_b64 s[28:29], -1
	s_sleep 2
	s_cbranch_scc1 .LBB0_679
	global_load_dword v2, v0, s[16:17] sc1
	s_waitcnt vmcnt(0)
	v_cmp_eq_u32_e32 vcc, 0, v2
	s_cbranch_vccnz .LBB0_681
	s_mov_b64 s[28:29], 0
	s_mov_b64 s[26:27], -1

.LBB0_693:
	s_and_b32 s24, s30, 0xff
	s_cmp_lg_u32 s24, 0
	s_mov_b64 s[26:27], -1
	s_sleep 2
	s_cbranch_scc1 .LBB0_696
	global_load_dword v1, v0, s[16:17] sc1
	s_waitcnt vmcnt(0)
	v_cmp_eq_u32_e32 vcc, 0, v1
	s_cbranch_vccnz .LBB0_698
	s_mov_b64 s[26:27], 0
	s_mov_b64 s[24:25], -1

.LBB0_848:
	global_load_dword v15, v16, s[6:7] sc1
	s_waitcnt lgkmcnt(0)
	global_load_dword v0, v16, s[8:9] sc1
	global_load_dword v1, v16, s[10:11] sc1
	global_load_dword v2, v16, s[16:17] sc1
	global_load_dword v3, v16, s[18:19] sc1
	global_load_dword v4, v16, s[20:21] sc1
	global_load_dword v5, v16, s[22:23] sc1
	global_load_dword v6, v16, s[24:25] sc1
	global_load_dword v7, v16, s[26:27] sc1
	global_load_dword v8, v16, s[28:29] sc1
	global_load_dword v9, v16, s[30:31] sc1
	global_load_dword v10, v16, s[34:35] sc1
	global_load_dword v11, v16, s[36:37] sc1
	global_load_dword v12, v16, s[38:39] sc1
	global_load_dword v13, v16, s[40:41] sc1
	global_load_dword v14, v16, s[42:43] sc1
	s_mov_b64 s[44:45], -1
	s_mov_b64 s[46:47], -1
	s_waitcnt vmcnt(14)
	v_add_u32_e32 v17, v0, v15
	s_waitcnt vmcnt(13)
	v_add_u32_e32 v17, v17, v1
	s_waitcnt vmcnt(12)
	v_add_u32_e32 v17, v17, v2
	s_waitcnt vmcnt(11)
	v_add_u32_e32 v17, v17, v3
	s_waitcnt vmcnt(10)
	v_add_u32_e32 v17, v17, v4
	s_waitcnt vmcnt(9)
	v_add_u32_e32 v17, v17, v5
	s_waitcnt vmcnt(8)
	v_add_u32_e32 v17, v17, v6
	s_waitcnt vmcnt(7)
	v_add_u32_e32 v17, v17, v7
	s_waitcnt vmcnt(6)
	v_add_u32_e32 v17, v17, v8
	s_waitcnt vmcnt(5)
	v_add_u32_e32 v17, v17, v9
	s_waitcnt vmcnt(4)
	v_add_u32_e32 v17, v17, v10
	s_waitcnt vmcnt(3)
	v_add_u32_e32 v17, v17, v11
	s_waitcnt vmcnt(2)
	v_add_u32_e32 v17, v17, v12
	s_waitcnt vmcnt(1)
	v_add_u32_e32 v17, v17, v13
	s_waitcnt vmcnt(0)
	v_add_u32_e32 v17, v17, v14
	v_cmp_eq_u32_e32 vcc, s33, v17
	s_cbranch_vccnz .LBB0_847
	s_and_b32 s44, s50, 0xff
	s_cmp_eq_u32 s44, 0
	s_mov_b64 s[44:45], -1
	s_mov_b64 s[48:49], -1
	s_sleep 2
	s_cbranch_scc0 .LBB0_852
	global_load_dword v17, v16, s[4:5] sc1
	s_waitcnt vmcnt(0)
	v_cmp_eq_u32_e32 vcc, 0, v17
	s_cbranch_vccnz .LBB0_854
	s_mov_b64 s[48:49], 0

.LBB0_866:
	s_and_b32 s24, s28, 0xff
	s_mov_b64 s[22:23], -1
	s_cmp_lg_u32 s24, 0
	s_mov_b64 s[26:27], -1
	s_sleep 2
	s_cbranch_scc1 .LBB0_869
	global_load_dword v2, v0, s[10:11] sc1
	s_waitcnt vmcnt(0)
	v_cmp_eq_u32_e32 vcc, 0, v2
	s_cbranch_vccnz .LBB0_871
	s_mov_b64 s[26:27], 0
	s_mov_b64 s[24:25], -1

.LBB0_883:
	s_and_b32 s22, s28, 0xff
	s_cmp_lg_u32 s22, 0
	s_mov_b64 s[24:25], -1
	s_sleep 2
	s_cbranch_scc1 .LBB0_886
	global_load_dword v1, v0, s[10:11] sc1
	s_waitcnt vmcnt(0)
	v_cmp_eq_u32_e32 vcc, 0, v1
	s_cbranch_vccnz .LBB0_888
	s_mov_b64 s[24:25], 0
	s_mov_b64 s[22:23], -1

.LBB0_956:
	global_load_dword v15, v16, s[6:7] sc1
	s_waitcnt lgkmcnt(0)
	global_load_dword v0, v16, s[8:9] sc1
	global_load_dword v1, v16, s[10:11] sc1
	global_load_dword v2, v16, s[16:17] sc1
	global_load_dword v3, v16, s[20:21] sc1
	global_load_dword v4, v16, s[22:23] sc1
	global_load_dword v5, v16, s[24:25] sc1
	global_load_dword v6, v16, s[26:27] sc1
	global_load_dword v7, v16, s[28:29] sc1
	global_load_dword v8, v16, s[30:31] sc1
	global_load_dword v9, v16, s[34:35] sc1
	global_load_dword v10, v16, s[36:37] sc1
	global_load_dword v11, v16, s[38:39] sc1
	global_load_dword v12, v16, s[40:41] sc1
	global_load_dword v13, v16, s[42:43] sc1
	global_load_dword v14, v16, s[44:45] sc1
	s_mov_b64 s[46:47], -1
	s_mov_b64 s[48:49], -1
	s_waitcnt vmcnt(14)
	v_add_u32_e32 v17, v0, v15
	s_waitcnt vmcnt(13)
	v_add_u32_e32 v17, v17, v1
	s_waitcnt vmcnt(12)
	v_add_u32_e32 v17, v17, v2
	s_waitcnt vmcnt(11)
	v_add_u32_e32 v17, v17, v3
	s_waitcnt vmcnt(10)
	v_add_u32_e32 v17, v17, v4
	s_waitcnt vmcnt(9)
	v_add_u32_e32 v17, v17, v5
	s_waitcnt vmcnt(8)
	v_add_u32_e32 v17, v17, v6
	s_waitcnt vmcnt(7)
	v_add_u32_e32 v17, v17, v7
	s_waitcnt vmcnt(6)
	v_add_u32_e32 v17, v17, v8
	s_waitcnt vmcnt(5)
	v_add_u32_e32 v17, v17, v9
	s_waitcnt vmcnt(4)
	v_add_u32_e32 v17, v17, v10
	s_waitcnt vmcnt(3)
	v_add_u32_e32 v17, v17, v11
	s_waitcnt vmcnt(2)
	v_add_u32_e32 v17, v17, v12
	s_waitcnt vmcnt(1)
	v_add_u32_e32 v17, v17, v13
	s_waitcnt vmcnt(0)
	v_add_u32_e32 v17, v17, v14
	v_cmp_eq_u32_e32 vcc, s33, v17
	s_cbranch_vccnz .LBB0_955
	s_and_b32 s46, s52, 0xff
	s_cmp_eq_u32 s46, 0
	s_mov_b64 s[46:47], -1
	s_mov_b64 s[50:51], -1
	s_sleep 2
	s_cbranch_scc0 .LBB0_960
	global_load_dword v17, v16, s[4:5] sc1
	s_waitcnt vmcnt(0)
	v_cmp_eq_u32_e32 vcc, 0, v17
	s_cbranch_vccnz .LBB0_962
	s_mov_b64 s[50:51], 0

.LBB0_974:
	s_and_b32 s26, s30, 0xff
	s_mov_b64 s[24:25], -1
	s_cmp_lg_u32 s26, 0
	s_mov_b64 s[28:29], -1
	s_sleep 2
	s_cbranch_scc1 .LBB0_977
	global_load_dword v2, v0, s[10:11] sc1
	s_waitcnt vmcnt(0)
	v_cmp_eq_u32_e32 vcc, 0, v2
	s_cbranch_vccnz .LBB0_979
	s_mov_b64 s[28:29], 0
	s_mov_b64 s[26:27], -1

.LBB0_991:
	s_and_b32 s24, s30, 0xff
	s_cmp_lg_u32 s24, 0
	s_mov_b64 s[26:27], -1
	s_sleep 2
	s_cbranch_scc1 .LBB0_994
	global_load_dword v1, v0, s[10:11] sc1
	s_waitcnt vmcnt(0)
	v_cmp_eq_u32_e32 vcc, 0, v1
	s_cbranch_vccnz .LBB0_996
	s_mov_b64 s[26:27], 0
	s_mov_b64 s[24:25], -1

.LBB0_1023:
	global_load_dword v15, v16, s[6:7] sc1
	s_waitcnt lgkmcnt(0)
	global_load_dword v0, v16, s[8:9] sc1
	global_load_dword v1, v16, s[10:11] sc1
	global_load_dword v2, v16, s[18:19] sc1
	global_load_dword v3, v16, s[20:21] sc1
	global_load_dword v4, v16, s[22:23] sc1
	global_load_dword v5, v16, s[24:25] sc1
	global_load_dword v6, v16, s[26:27] sc1
	global_load_dword v7, v16, s[28:29] sc1
	global_load_dword v8, v16, s[30:31] sc1
	global_load_dword v9, v16, s[34:35] sc1
	global_load_dword v10, v16, s[36:37] sc1
	global_load_dword v11, v16, s[38:39] sc1
	global_load_dword v12, v16, s[40:41] sc1
	global_load_dword v13, v16, s[42:43] sc1
	global_load_dword v14, v16, s[44:45] sc1
	s_mov_b64 s[46:47], -1
	s_mov_b64 s[48:49], -1
	s_waitcnt vmcnt(14)
	v_add_u32_e32 v17, v0, v15
	s_waitcnt vmcnt(13)
	v_add_u32_e32 v17, v17, v1
	s_waitcnt vmcnt(12)
	v_add_u32_e32 v17, v17, v2
	s_waitcnt vmcnt(11)
	v_add_u32_e32 v17, v17, v3
	s_waitcnt vmcnt(10)
	v_add_u32_e32 v17, v17, v4
	s_waitcnt vmcnt(9)
	v_add_u32_e32 v17, v17, v5
	s_waitcnt vmcnt(8)
	v_add_u32_e32 v17, v17, v6
	s_waitcnt vmcnt(7)
	v_add_u32_e32 v17, v17, v7
	s_waitcnt vmcnt(6)
	v_add_u32_e32 v17, v17, v8
	s_waitcnt vmcnt(5)
	v_add_u32_e32 v17, v17, v9
	s_waitcnt vmcnt(4)
	v_add_u32_e32 v17, v17, v10
	s_waitcnt vmcnt(3)
	v_add_u32_e32 v17, v17, v11
	s_waitcnt vmcnt(2)
	v_add_u32_e32 v17, v17, v12
	s_waitcnt vmcnt(1)
	v_add_u32_e32 v17, v17, v13
	s_waitcnt vmcnt(0)
	v_add_u32_e32 v17, v17, v14
	v_cmp_eq_u32_e32 vcc, s33, v17
	s_cbranch_vccnz .LBB0_1022
	s_and_b32 s46, s52, 0xff
	s_cmp_eq_u32 s46, 0
	s_mov_b64 s[46:47], -1
	s_mov_b64 s[50:51], -1
	s_sleep 2
	s_cbranch_scc0 .LBB0_1027
	global_load_dword v17, v16, s[4:5] sc1
	s_waitcnt vmcnt(0)
	v_cmp_eq_u32_e32 vcc, 0, v17
	s_cbranch_vccnz .LBB0_1029
	s_mov_b64 s[50:51], 0

.LBB0_1201:
	global_load_dword v15, v16, s[4:5] sc1
	s_waitcnt lgkmcnt(0)
	global_load_dword v0, v16, s[6:7] sc1
	global_load_dword v1, v16, s[8:9] sc1
	global_load_dword v2, v16, s[10:11] sc1
	global_load_dword v3, v16, s[16:17] sc1
	global_load_dword v4, v16, s[18:19] sc1
	global_load_dword v5, v16, s[20:21] sc1
	global_load_dword v6, v16, s[22:23] sc1
	global_load_dword v7, v16, s[24:25] sc1
	global_load_dword v8, v16, s[26:27] sc1
	global_load_dword v9, v16, s[28:29] sc1
	global_load_dword v10, v16, s[30:31] sc1
	global_load_dword v11, v16, s[34:35] sc1
	global_load_dword v12, v16, s[36:37] sc1
	global_load_dword v13, v16, s[38:39] sc1
	global_load_dword v14, v16, s[40:41] sc1
	s_mov_b64 s[42:43], -1
	s_mov_b64 s[44:45], -1
	s_waitcnt vmcnt(14)
	v_add_u32_e32 v17, v0, v15
	s_waitcnt vmcnt(13)
	v_add_u32_e32 v17, v17, v1
	s_waitcnt vmcnt(12)
	v_add_u32_e32 v17, v17, v2
	s_waitcnt vmcnt(11)
	v_add_u32_e32 v17, v17, v3
	s_waitcnt vmcnt(10)
	v_add_u32_e32 v17, v17, v4
	s_waitcnt vmcnt(9)
	v_add_u32_e32 v17, v17, v5
	s_waitcnt vmcnt(8)
	v_add_u32_e32 v17, v17, v6
	s_waitcnt vmcnt(7)
	v_add_u32_e32 v17, v17, v7
	s_waitcnt vmcnt(6)
	v_add_u32_e32 v17, v17, v8
	s_waitcnt vmcnt(5)
	v_add_u32_e32 v17, v17, v9
	s_waitcnt vmcnt(4)
	v_add_u32_e32 v17, v17, v10
	s_waitcnt vmcnt(3)
	v_add_u32_e32 v17, v17, v11
	s_waitcnt vmcnt(2)
	v_add_u32_e32 v17, v17, v12
	s_waitcnt vmcnt(1)
	v_add_u32_e32 v17, v17, v13
	s_waitcnt vmcnt(0)
	v_add_u32_e32 v17, v17, v14
	v_cmp_eq_u32_e32 vcc, s33, v17
	s_cbranch_vccnz .LBB0_1200
	s_and_b32 s42, s48, 0xff
	s_cmp_eq_u32 s42, 0
	s_mov_b64 s[42:43], -1
	s_mov_b64 s[46:47], -1
	s_sleep 2
	s_cbranch_scc0 .LBB0_1205
	global_load_dword v17, v16, s[2:3] sc1
	s_waitcnt vmcnt(0)
	v_cmp_eq_u32_e32 vcc, 0, v17
	s_cbranch_vccnz .LBB0_1207
	s_mov_b64 s[46:47], 0

.LBB0_1219:
	s_and_b32 s22, s26, 0xff
	s_mov_b64 s[20:21], -1
	s_cmp_lg_u32 s22, 0
	s_mov_b64 s[24:25], -1
	s_sleep 2
	s_cbranch_scc1 .LBB0_1222
	global_load_dword v2, v0, s[8:9] sc1
	s_waitcnt vmcnt(0)
	v_cmp_eq_u32_e32 vcc, 0, v2
	s_cbranch_vccnz .LBB0_1224
	s_mov_b64 s[24:25], 0
	s_mov_b64 s[22:23], -1

.LBB0_1236:
	s_and_b32 s20, s26, 0xff
	s_cmp_lg_u32 s20, 0
	s_mov_b64 s[22:23], -1
	s_sleep 2
	s_cbranch_scc1 .LBB0_1239
	global_load_dword v1, v0, s[8:9] sc1
	s_waitcnt vmcnt(0)
	v_cmp_eq_u32_e32 vcc, 0, v1
	s_cbranch_vccnz .LBB0_1241
	s_mov_b64 s[22:23], 0
	s_mov_b64 s[20:21], -1
